# norm2 row loop: previous row's stores drained before (not after) the row's shift/scale loads are issued
# speedup vs baseline: 1.0077x; 1.0077x over previous
; __device__ __forceinline__ unsigned cvt_pk_bf16(float lo, float hi) { unsigned r; asm("v_cvt_pk_bf16_f32 %0, %1, %2" : "=v"(r) : "v"(lo), "v"(hi)); return r; }
; __device__ __forceinline__ void norm_rows(const Ctx& F, CParams& P, int layer, int which  , int t_first, int t_end, int t_stride) {
;     ...
;     for (int t = t_first; t < t_end; t += t_stride) {
;         const int vs = vsel_of_row(t);
;         const float* shf = mod + (size_t)vs * 12288 + (which ? 3 : 0) * DM; const float* scl = shf + DM;
;         f32x4 v[8], sc[8], sh[8]; float ss = 0.f;
; #pragma unroll
;         for (int j = 0; j < 8; ++j) { v[j] = vn[j]; sc[j] = *(const f32x4*)(scl + j * 256 + lane * 4); sh[j] = *(const f32x4*)(shf + j * 256 + lane * 4); }
;         { const int tn = t + t_stride; const float* src = srcrow(tn < t_end ? tn : t);
; #pragma unroll
;           for (int j = 0; j < 8; ++j) vn[j] = *(const f32x4*)(src + j * 256 + lane * 4); }
; #pragma unroll
;         for (int j = 0; j < 8; ++j) ss += v[j][0] * v[j][0] + v[j][1] * v[j][1] + v[j][2] * v[j][2] + v[j][3] * v[j][3];
;         ss = wave_sum(ss);
;         const float rstd = rsqrtf(ss * (1.f / DM) + EPS);
; #pragma unroll
;         for (int j = 0; j < 8; ++j) { const int c = j * 256 + lane * 4;
;             f32x4 y;
; #pragma unroll
;             for (int e = 0; e < 4; ++e) y[e] = (v[j][e] * rstd * g[j][e]) * (1.f + sc[j][e]) + sh[j][e];
;             u32x2 w; w.x = cvt_pk_bf16(y[0], y[1]); w.y = cvt_pk_bf16(y[2], y[3]);
;             *(u32x2*)(H + (size_t)t * DM + c) = w; }
.LBB0_2646:
	s_cmpk_lt_u32 s2, 0x4000
	s_cselect_b32 s1, s95, 0x6000
	s_cmpk_gt_i32 s2, 0x1fff
	s_cselect_b32 s1, s1, 0
	s_lshl_b32 s1, s1, 2
	s_add_u32 s10, s8, s1
	s_addc_u32 s11, s9, 0
	v_lshl_add_u64 v[66:67], v[162:163], 2, s[10:11]
	v_add_co_u32_e32 v70, vcc, s95, v66
	v_lshl_add_u64 v[68:69], v[66:67], 0, s[42:43]
	s_nop 0
	v_addc_co_u32_e32 v71, vcc, 0, v67, vcc
	s_waitcnt vmcnt(0)
	global_load_dwordx4 v[158:161], v[70:71], off offset:-4096
	global_load_dwordx4 v[154:157], v[66:67], off
	global_load_dwordx4 v[150:153], v[68:69], off offset:1024
	global_load_dwordx4 v[146:149], v[66:67], off offset:1024
	global_load_dwordx4 v[142:145], v[68:69], off offset:2048
	global_load_dwordx4 v[138:141], v[66:67], off offset:2048
	global_load_dwordx4 v[134:137], v[68:69], off offset:3072
	global_load_dwordx4 v[130:133], v[66:67], off offset:3072
	global_load_dwordx4 v[122:125], v[70:71], off
	s_waitcnt vmcnt(9)
	v_mul_f32_e32 v32, v63, v63
	v_mul_f32_e32 v168, v59, v59
	v_fmac_f32_e32 v32, v62, v62
	v_fmac_f32_e32 v168, v58, v58
	v_fmac_f32_e32 v32, v64, v64
	v_fmac_f32_e32 v168, v60, v60
	v_fmac_f32_e32 v32, v65, v65
	v_fmac_f32_e32 v168, v61, v61
	v_add_f32_e32 v32, v32, v168
	v_mul_f32_e32 v168, v55, v55
	v_fmac_f32_e32 v168, v54, v54
	v_fmac_f32_e32 v168, v56, v56
	v_fmac_f32_e32 v168, v57, v57
	v_add_f32_e32 v32, v32, v168
	v_mul_f32_e32 v168, v51, v51
	v_fmac_f32_e32 v168, v50, v50
	v_fmac_f32_e32 v168, v52, v52
	v_fmac_f32_e32 v168, v53, v53
	v_add_f32_e32 v32, v32, v168
	v_mul_f32_e32 v168, v47, v47
	v_add_co_u32_e32 v66, vcc, s81, v66
	v_fmac_f32_e32 v168, v46, v46
	s_nop 0
	v_addc_co_u32_e32 v67, vcc, 0, v67, vcc
	s_add_i32 s1, s2, s0
	v_fmac_f32_e32 v168, v48, v48
	global_load_dwordx4 v[126:129], v[66:67], off
	global_load_dwordx4 v[118:121], v[70:71], off offset:1024
	global_load_dwordx4 v[114:117], v[66:67], off offset:1024
	global_load_dwordx4 v[110:113], v[70:71], off offset:2048
	global_load_dwordx4 v[106:109], v[66:67], off offset:2048
	s_nop 0
	global_load_dwordx4 v[70:73], v[70:71], off offset:3072
	s_nop 0
	global_load_dwordx4 v[66:69], v[66:67], off offset:3072
	s_cmp_lt_i32 s1, s7
	v_fmac_f32_e32 v168, v49, v49
	s_cselect_b64 s[10:11], -1, 0
	v_add_f32_e32 v32, v32, v168
	v_mul_f32_e32 v168, v43, v43
	s_and_b64 vcc, s[10:11], exec
	v_fmac_f32_e32 v168, v42, v42
	s_cselect_b32 s2, s1, s2
	v_fmac_f32_e32 v168, v44, v44
	s_ashr_i32 s3, s2, 31
	v_fmac_f32_e32 v168, v45, v45
	s_lshl_b64 s[2:3], s[2:3], 13
	v_add_f32_e32 v32, v32, v168
	v_mul_f32_e32 v168, v39, v39
	v_lshl_add_u64 v[90:91], v[164:165], 0, s[2:3]
	v_fmac_f32_e32 v168, v38, v38
	v_add_co_u32_e64 v102, s[2:3], s81, v90
	v_fmac_f32_e32 v168, v40, v40
	s_nop 0
	v_addc_co_u32_e64 v103, s[2:3], 0, v91, s[2:3]
	v_fmac_f32_e32 v168, v41, v41
	global_load_dwordx4 v[74:77], v[90:91], off
	global_load_dwordx4 v[78:81], v[90:91], off offset:1024
	global_load_dwordx4 v[82:85], v[90:91], off offset:2048
	global_load_dwordx4 v[86:89], v[90:91], off offset:3072
	s_nop 0
	global_load_dwordx4 v[90:93], v[102:103], off
	global_load_dwordx4 v[94:97], v[102:103], off offset:1024
	global_load_dwordx4 v[98:101], v[102:103], off offset:2048
	s_nop 0
	global_load_dwordx4 v[102:105], v[102:103], off offset:3072
	v_add_f32_e32 v32, v32, v168
	v_mul_f32_e32 v168, v35, v35
	v_fmac_f32_e32 v168, v34, v34
	v_fmac_f32_e32 v168, v36, v36
	v_fmac_f32_e32 v168, v37, v37
	v_add_f32_e32 v32, v32, v168
	ds_swizzle_b32 v168, v32 offset:swizzle(SWAP,16)
	s_waitcnt lgkmcnt(0)
	v_add_f32_e32 v32, v32, v168
	ds_swizzle_b32 v168, v32 offset:swizzle(SWAP,8)
	s_waitcnt lgkmcnt(0)
	v_add_f32_e32 v32, v32, v168
	ds_swizzle_b32 v168, v32 offset:swizzle(SWAP,4)
	s_waitcnt vmcnt(23)
	v_add_f32_e32 v158, 1.0, v158
	s_waitcnt lgkmcnt(0)
	v_add_f32_e32 v32, v32, v168
	ds_swizzle_b32 v168, v32 offset:swizzle(SWAP,2)
	s_waitcnt lgkmcnt(0)
	v_add_f32_e32 v32, v32, v168
	ds_swizzle_b32 v168, v32 offset:swizzle(SWAP,1)
	s_waitcnt lgkmcnt(0)
	v_add_f32_e32 v32, v32, v168
	v_mov_b32_e32 v168, v32
	s_nop 1
	v_permlane32_swap_b32_e32 v32, v168
	v_add_f32_e32 v32, v32, v168
	v_fmamk_f32 v32, v32, 0x3a000000, v234
	v_cmp_gt_f32_e64 s[2:3], s57, v32
	v_mul_f32_e32 v168, 0x4b800000, v32
	s_nop 0
	v_cndmask_b32_e64 v32, v32, v168, s[2:3]
	v_rsq_f32_e32 v32, v32
	s_nop 0
	v_mul_f32_e32 v168, 0x45800000, v32
	v_cndmask_b32_e64 v32, v32, v168, s[2:3]
	v_mul_f32_e32 v62, v62, v32
	v_mul_f32_e32 v62, v0, v62
	v_mul_f32_e32 v63, v63, v32
	s_waitcnt vmcnt(22)
	v_fma_f32 v62, v158, v62, v154
	v_mul_f32_e32 v63, v1, v63
	v_add_f32_e32 v154, 1.0, v159
	v_mul_f32_e32 v64, v64, v32
	v_fma_f32 v63, v154, v63, v155
	v_mul_f32_e32 v64, v2, v64
	v_add_f32_e32 v154, 1.0, v160
	v_mul_f32_e32 v65, v65, v32
	v_fma_f32 v64, v154, v64, v156
	v_mul_f32_e32 v65, v3, v65
	v_add_f32_e32 v154, 1.0, v161
	v_cvt_pk_bf16_f32 v62, v62, v63
	v_mul_f32_e32 v58, v58, v32
	v_fmac_f32_e32 v157, v154, v65
	v_cvt_pk_bf16_f32 v63, v64, v157
	global_store_dwordx2 v[166:167], v[62:63], off
	v_mul_f32_e32 v58, v4, v58
	s_waitcnt vmcnt(22)
	v_add_f32_e32 v62, 1.0, v150
	v_mul_f32_e32 v59, v59, v32
	s_waitcnt vmcnt(21)
; __device__ __forceinline__ unsigned cvt_pk_bf16(float lo, float hi) { unsigned r; asm("v_cvt_pk_bf16_f32 %0, %1, %2" : "=v"(r) : "v"(lo), "v"(hi)); return r; }
; __device__ __forceinline__ void norm_rows(const Ctx& F, CParams& P, int layer, int which  , int t_first, int t_end, int t_stride) {
;     ...
;         { const int tn = t + t_stride; const float* src = srcrow(tn < t_end ? tn : t);
; #pragma unroll
;           for (int j = 0; j < 8; ++j) vn[j] = *(const f32x4*)(src + j * 256 + lane * 4); }
; #pragma unroll
;         for (int j = 0; j < 8; ++j) ss += v[j][0] * v[j][0] + v[j][1] * v[j][1] + v[j][2] * v[j][2] + v[j][3] * v[j][3];
;         ss = wave_sum(ss);
;         const float rstd = rsqrtf(ss * (1.f / DM) + EPS);
; #pragma unroll
;         for (int j = 0; j < 8; ++j) { const int c = j * 256 + lane * 4;
;             f32x4 y;
; #pragma unroll
;             for (int e = 0; e < 4; ++e) y[e] = (v[j][e] * rstd * g[j][e]) * (1.f + sc[j][e]) + sh[j][e];
;             u32x2 w; w.x = cvt_pk_bf16(y[0], y[1]); w.y = cvt_pk_bf16(y[2], y[3]);
;             *(u32x2*)(H + (size_t)t * DM + c) = w; }
	v_fma_f32 v58, v62, v58, v146
	v_mul_f32_e32 v59, v5, v59
	v_add_f32_e32 v62, 1.0, v151
	v_mul_f32_e32 v60, v60, v32
	v_fma_f32 v59, v62, v59, v147
	v_mul_f32_e32 v60, v6, v60
	v_add_f32_e32 v62, 1.0, v152
	v_mul_f32_e32 v61, v61, v32
	v_fma_f32 v60, v62, v60, v148
	v_mul_f32_e32 v61, v7, v61
	v_add_f32_e32 v62, 1.0, v153
	v_cvt_pk_bf16_f32 v58, v58, v59
	v_mul_f32_e32 v54, v54, v32
	v_fmac_f32_e32 v149, v62, v61
	v_cvt_pk_bf16_f32 v59, v60, v149
	global_store_dwordx2 v[166:167], v[58:59], off offset:512
	v_mul_f32_e32 v54, v8, v54
	s_waitcnt vmcnt(21)
	v_add_f32_e32 v58, 1.0, v142
	v_mul_f32_e32 v55, v55, v32
	s_waitcnt vmcnt(20)
	v_fma_f32 v54, v58, v54, v138
	v_mul_f32_e32 v55, v9, v55
	v_add_f32_e32 v58, 1.0, v143
	v_mul_f32_e32 v56, v56, v32
	v_fma_f32 v55, v58, v55, v139
	v_mul_f32_e32 v56, v10, v56
	v_add_f32_e32 v58, 1.0, v144
	v_mul_f32_e32 v57, v57, v32
	v_fma_f32 v56, v58, v56, v140
	v_mul_f32_e32 v57, v11, v57
	v_add_f32_e32 v58, 1.0, v145
	v_cvt_pk_bf16_f32 v54, v54, v55
	v_mul_f32_e32 v50, v50, v32
	v_fmac_f32_e32 v141, v58, v57
	v_cvt_pk_bf16_f32 v55, v56, v141
	global_store_dwordx2 v[166:167], v[54:55], off offset:1024
	v_mul_f32_e32 v50, v12, v50
	s_waitcnt vmcnt(20)
	v_add_f32_e32 v54, 1.0, v134
	v_mul_f32_e32 v51, v51, v32
	s_waitcnt vmcnt(19)
	v_fma_f32 v50, v54, v50, v130
	v_mul_f32_e32 v51, v13, v51
	v_add_f32_e32 v54, 1.0, v135
	v_mul_f32_e32 v52, v52, v32
	v_fma_f32 v51, v54, v51, v131
	v_mul_f32_e32 v52, v14, v52
	v_add_f32_e32 v54, 1.0, v136
	v_mul_f32_e32 v53, v53, v32
	v_fma_f32 v52, v54, v52, v132
	v_mul_f32_e32 v53, v15, v53
	v_add_f32_e32 v54, 1.0, v137
	v_cvt_pk_bf16_f32 v50, v50, v51
	v_mul_f32_e32 v46, v46, v32
	v_fmac_f32_e32 v133, v54, v53
	v_cvt_pk_bf16_f32 v51, v52, v133
	global_store_dwordx2 v[166:167], v[50:51], off offset:1536
	v_mul_f32_e32 v46, v16, v46
	s_waitcnt vmcnt(19)
	v_add_f32_e32 v50, 1.0, v122
	v_mul_f32_e32 v47, v47, v32
	s_waitcnt vmcnt(18)
	v_fma_f32 v46, v50, v46, v126
	v_mul_f32_e32 v47, v17, v47
	v_add_f32_e32 v50, 1.0, v123
	v_mul_f32_e32 v48, v48, v32
	v_fma_f32 v47, v50, v47, v127
	v_mul_f32_e32 v48, v18, v48
	v_add_f32_e32 v50, 1.0, v124
	v_mul_f32_e32 v49, v49, v32
	v_fma_f32 v48, v50, v48, v128
	v_mul_f32_e32 v49, v19, v49
	v_add_f32_e32 v50, 1.0, v125
	v_cvt_pk_bf16_f32 v46, v46, v47
	v_mul_f32_e32 v42, v42, v32
	v_fmac_f32_e32 v129, v50, v49
	v_cvt_pk_bf16_f32 v47, v48, v129
	global_store_dwordx2 v[166:167], v[46:47], off offset:2048
	v_mul_f32_e32 v42, v20, v42
	s_waitcnt vmcnt(18)
	v_add_f32_e32 v46, 1.0, v118
	v_mul_f32_e32 v43, v43, v32
	s_waitcnt vmcnt(17)
	v_fma_f32 v42, v46, v42, v114
	v_mul_f32_e32 v43, v21, v43
	v_add_f32_e32 v46, 1.0, v119
	v_mul_f32_e32 v44, v44, v32
	v_fma_f32 v43, v46, v43, v115
	v_mul_f32_e32 v44, v22, v44
	v_add_f32_e32 v46, 1.0, v120
	v_mul_f32_e32 v45, v45, v32
	v_fma_f32 v44, v46, v44, v116
	v_mul_f32_e32 v45, v23, v45
	v_add_f32_e32 v46, 1.0, v121
	v_cvt_pk_bf16_f32 v42, v42, v43
	v_mul_f32_e32 v38, v38, v32
	v_fmac_f32_e32 v117, v46, v45
	v_cvt_pk_bf16_f32 v43, v44, v117
	global_store_dwordx2 v[166:167], v[42:43], off offset:2560
	v_mul_f32_e32 v38, v24, v38
	s_waitcnt vmcnt(17)
	v_add_f32_e32 v42, 1.0, v110
	v_mul_f32_e32 v39, v39, v32
	s_waitcnt vmcnt(16)
	v_fma_f32 v38, v42, v38, v106
	v_mul_f32_e32 v39, v25, v39
	v_add_f32_e32 v42, 1.0, v111
	v_mul_f32_e32 v40, v40, v32
	v_fma_f32 v39, v42, v39, v107
	v_mul_f32_e32 v40, v26, v40
	v_add_f32_e32 v42, 1.0, v112
	v_mul_f32_e32 v41, v41, v32
	v_fma_f32 v40, v42, v40, v108
	v_mul_f32_e32 v41, v27, v41
	v_add_f32_e32 v42, 1.0, v113
	v_cvt_pk_bf16_f32 v38, v38, v39
	v_mul_f32_e32 v34, v34, v32
	v_fmac_f32_e32 v109, v42, v41
	v_cvt_pk_bf16_f32 v39, v40, v109
	global_store_dwordx2 v[166:167], v[38:39], off offset:3072
	v_mul_f32_e32 v34, v28, v34
	s_waitcnt vmcnt(16)
	v_add_f32_e32 v38, 1.0, v70
	v_mul_f32_e32 v35, v35, v32
	s_waitcnt vmcnt(15)
	v_fma_f32 v34, v38, v34, v66
	v_mul_f32_e32 v35, v29, v35
	v_add_f32_e32 v38, 1.0, v71
	v_mul_f32_e32 v36, v36, v32
	v_mul_f32_e32 v32, v37, v32
	v_fma_f32 v35, v38, v35, v67
	v_mul_f32_e32 v36, v30, v36
	v_add_f32_e32 v38, 1.0, v72
	v_mul_f32_e32 v32, v31, v32
	v_add_f32_e32 v37, 1.0, v73
	v_fma_f32 v36, v38, v36, v68
	v_fmac_f32_e32 v69, v37, v32
	v_cvt_pk_bf16_f32 v34, v34, v35
	v_cvt_pk_bf16_f32 v35, v36, v69
	global_store_dwordx2 v[166:167], v[34:35], off offset:3584
	s_waitcnt vmcnt(15)
	v_mov_b64_e32 v[62:63], v[74:75]
	s_waitcnt vmcnt(14)
	v_mov_b64_e32 v[58:59], v[78:79]
	s_waitcnt vmcnt(13)
	v_mov_b64_e32 v[54:55], v[82:83]
	s_waitcnt vmcnt(12)
	v_mov_b64_e32 v[50:51], v[86:87]
	s_waitcnt vmcnt(11)
	v_mov_b64_e32 v[46:47], v[90:91]
	s_waitcnt vmcnt(10)
	v_mov_b64_e32 v[42:43], v[94:95]
	s_waitcnt vmcnt(9)
	v_mov_b64_e32 v[38:39], v[98:99]
	s_waitcnt vmcnt(8)
	v_mov_b64_e32 v[34:35], v[102:103]
	v_lshl_add_u64 v[166:167], v[166:167], 0, s[4:5]
	v_mov_b64_e32 v[64:65], v[76:77]
	v_mov_b64_e32 v[60:61], v[80:81]
	v_mov_b64_e32 v[56:57], v[84:85]
	v_mov_b64_e32 v[52:53], v[88:89]
	v_mov_b64_e32 v[48:49], v[92:93]
	v_mov_b64_e32 v[44:45], v[96:97]
	v_mov_b64_e32 v[40:41], v[100:101]
	v_mov_b64_e32 v[36:37], v[104:105]
	s_mov_b32 s2, s1
	s_cbranch_vccnz .LBB0_2646
	s_mov_b32 s66, 0x20000
